# v14 + phase G: per-row rstd statistics prefetched in the tile preheader instead of two exposed load round trips at the top of each epilogue
# baseline (speedup 1.0000x reference)
.LBB0_772:
	s_ashr_i32 s61, s60, 31
	s_lshl_b64 s[12:13], s[60:61], 20
	s_add_u32 s78, s37, s12
	s_addc_u32 s79, s40, s13
	s_and_b64 s[12:13], s[10:11], exec
	s_cselect_b32 s61, s79, s7
	s_cselect_b32 vcc_lo, s78, s6
	s_ashr_i32 s35, s34, 31
	s_lshl_b64 s[12:13], s[34:35], 20
	s_add_u32 s22, s1, s12
	s_addc_u32 s23, s0, s13
	s_and_b64 s[12:13], s[10:11], exec
	s_cselect_b32 s35, s23, s17
	s_cselect_b32 vcc_hi, s22, s16
	s_add_u32 s16, s16, 0x100
	s_addc_u32 s17, s17, 0
	s_add_u32 s12, s6, 0x80080
	v_mov_b32_e32 v26, 0
	s_addc_u32 s13, s7, 0
	s_mov_b32 s18, -2
	v_mov_b32_e32 v27, v26
	v_mov_b32_e32 v28, v26
	v_mov_b32_e32 v29, v26
	v_mov_b32_e32 v82, v26
	v_mov_b32_e32 v83, v26
	v_mov_b32_e32 v84, v26
	v_mov_b32_e32 v85, v26
	v_mov_b32_e32 v2, v26
	v_mov_b32_e32 v3, v26
	v_mov_b32_e32 v4, v26
	v_mov_b32_e32 v5, v26
	v_mov_b32_e32 v58, v26
	v_mov_b32_e32 v59, v26
	v_mov_b32_e32 v60, v26
	v_mov_b32_e32 v61, v26
	v_mov_b32_e32 v6, v26
	v_mov_b32_e32 v7, v26
	v_mov_b32_e32 v8, v26
	v_mov_b32_e32 v9, v26
	v_mov_b32_e32 v62, v26
	v_mov_b32_e32 v63, v26
	v_mov_b32_e32 v64, v26
	v_mov_b32_e32 v65, v26
	v_mov_b32_e32 v10, v26
	v_mov_b32_e32 v11, v26
	v_mov_b32_e32 v12, v26
	v_mov_b32_e32 v13, v26
	v_mov_b32_e32 v74, v26
	v_mov_b32_e32 v75, v26
	v_mov_b32_e32 v76, v26
	v_mov_b32_e32 v77, v26
	v_mov_b32_e32 v30, v26
	v_mov_b32_e32 v31, v26
	v_mov_b32_e32 v32, v26
	v_mov_b32_e32 v33, v26
	v_mov_b32_e32 v86, v26
	v_mov_b32_e32 v87, v26
	v_mov_b32_e32 v88, v26
	v_mov_b32_e32 v89, v26
	v_mov_b32_e32 v14, v26
	v_mov_b32_e32 v15, v26
	v_mov_b32_e32 v16, v26
	v_mov_b32_e32 v17, v26
	v_mov_b32_e32 v66, v26
	v_mov_b32_e32 v67, v26
	v_mov_b32_e32 v68, v26
	v_mov_b32_e32 v69, v26
	v_mov_b32_e32 v18, v26
	v_mov_b32_e32 v19, v26
	v_mov_b32_e32 v20, v26
	v_mov_b32_e32 v21, v26
	v_mov_b32_e32 v70, v26
	v_mov_b32_e32 v71, v26
	v_mov_b32_e32 v72, v26
	v_mov_b32_e32 v73, v26
	v_mov_b32_e32 v22, v26
	v_mov_b32_e32 v23, v26
	v_mov_b32_e32 v24, v26
	v_mov_b32_e32 v25, v26
	v_mov_b32_e32 v78, v26
	v_mov_b32_e32 v79, v26
	v_mov_b32_e32 v80, v26
	v_mov_b32_e32 v81, v26
	v_mov_b32_e32 v50, v26
	v_mov_b32_e32 v51, v26
	v_mov_b32_e32 v52, v26
	v_mov_b32_e32 v53, v26
	v_mov_b32_e32 v118, v26
	v_mov_b32_e32 v119, v26
	v_mov_b32_e32 v120, v26
	v_mov_b32_e32 v121, v26
	v_mov_b32_e32 v34, v26
	v_mov_b32_e32 v35, v26
	v_mov_b32_e32 v36, v26
	v_mov_b32_e32 v37, v26
	v_mov_b32_e32 v98, v26
	v_mov_b32_e32 v99, v26
	v_mov_b32_e32 v100, v26
	v_mov_b32_e32 v101, v26
	v_mov_b32_e32 v38, v26
	v_mov_b32_e32 v39, v26
	v_mov_b32_e32 v40, v26
	v_mov_b32_e32 v41, v26
	v_mov_b32_e32 v102, v26
	v_mov_b32_e32 v103, v26
	v_mov_b32_e32 v104, v26
	v_mov_b32_e32 v105, v26
	v_mov_b32_e32 v94, v26
	v_mov_b32_e32 v95, v26
	v_mov_b32_e32 v96, v26
	v_mov_b32_e32 v97, v26
	v_mov_b32_e32 v114, v26
	v_mov_b32_e32 v115, v26
	v_mov_b32_e32 v116, v26
	v_mov_b32_e32 v117, v26
	v_mov_b32_e32 v54, v26
	v_mov_b32_e32 v55, v26
	v_mov_b32_e32 v56, v26
	v_mov_b32_e32 v57, v26
	v_mov_b32_e32 v126, v26
	v_mov_b32_e32 v127, v26
	v_mov_b32_e32 v128, v26
	v_mov_b32_e32 v129, v26
	v_mov_b32_e32 v42, v26
	v_mov_b32_e32 v43, v26
	v_mov_b32_e32 v44, v26
	v_mov_b32_e32 v45, v26
	v_mov_b32_e32 v106, v26
	v_mov_b32_e32 v107, v26
	v_mov_b32_e32 v108, v26
	v_mov_b32_e32 v109, v26
	v_mov_b32_e32 v46, v26
	v_mov_b32_e32 v47, v26
	v_mov_b32_e32 v48, v26
	v_mov_b32_e32 v49, v26
	v_mov_b32_e32 v110, v26
	v_mov_b32_e32 v111, v26
	v_mov_b32_e32 v112, v26
	v_mov_b32_e32 v113, v26
	v_mov_b32_e32 v90, v26
	v_mov_b32_e32 v91, v26
	v_mov_b32_e32 v92, v26
	v_mov_b32_e32 v93, v26
	v_mov_b32_e32 v122, v26
	v_mov_b32_e32 v123, v26
	v_mov_b32_e32 v124, v26
	v_mov_b32_e32 v125, v26
	s_lshl_b32 s6, s91, 8
	s_add_i32 s6, s6, s86
	v_add_u32_e32 v218, s6, v206
	v_ashrrev_i32_e32 v219, 31, v218
	v_lshl_add_u64 v[218:219], v[218:219], 3, s[62:63]
	global_load_dwordx2 v[220:221], v[218:219], off
	global_load_dwordx2 v[222:223], v[218:219], off offset:128
	global_load_dwordx2 v[224:225], v[218:219], off offset:256
	global_load_dwordx2 v[226:227], v[218:219], off offset:384
	global_load_dwordx2 v[228:229], v[218:219], off offset:1024
	global_load_dwordx2 v[230:231], v[218:219], off offset:1152
	global_load_dwordx2 v[234:235], v[218:219], off offset:1280
	global_load_dwordx2 v[238:239], v[218:219], off offset:1408

.LBB0_776:
	s_lshl_b32 s6, s91, 8
	v_mov_b32_e32 v132, v206
	s_add_i32 s6, s6, s86
	v_mov_b32_e32 v154, v207
	v_add_u32_e32 v186, s6, v132
	v_ashrrev_i32_e32 v187, 31, v186
	v_lshl_add_u64 v[138:139], v[186:187], 3, s[62:63]
	v_mov_b64_e32 v[130:131], v[220:221]
	v_mov_b64_e32 v[198:199], v[222:223]
	v_mov_b64_e32 v[196:197], v[224:225]
	v_mov_b64_e32 v[134:135], v[226:227]
	s_lshl_b32 s6, s36, 7
	s_or_b32 s6, s6, s52
	v_lshl_add_u32 v188, v154, 3, s6
	v_lshlrev_b32_e32 v155, 2, v132
	s_waitcnt vmcnt(0)
	v_ffbh_u32_e32 v133, v135
	v_min_u32_e32 v133, 32, v133
	v_lshlrev_b64 v[134:135], v133, v[134:135]
	v_min_u32_e32 v134, 1, v134
	v_or_b32_e32 v134, v135, v134
	v_cvt_f32_u32_e32 v134, v134
	v_sub_u32_e32 v133, 32, v133
	v_ldexp_f32 v133, v134, v133
	v_mul_f32_e32 v133, 0x35800000, v133
	v_fmamk_f32 v133, v133, 0x3a000000, v232
	v_cmp_gt_f32_e32 vcc, s5, v133
	v_mul_f32_e32 v134, 0x4b800000, v133
	s_nop 0
	v_cndmask_b32_e32 v133, v133, v134, vcc
	v_rsq_f32_e32 v133, v133
	s_nop 0
	v_mul_f32_e32 v134, 0x45800000, v133
	v_cndmask_b32_e32 v140, v133, v134, vcc
	v_pk_mul_f32 v[134:135], v[126:127], v[140:141] op_sel_hi:[1,0]
	v_mov_b64_e32 v[194:195], v[228:229]
	v_mov_b64_e32 v[192:193], v[230:231]
	v_mov_b64_e32 v[190:191], v[234:235]
	v_mov_b64_e32 v[126:127], v[238:239]
	v_pk_mul_f32 v[136:137], v[128:129], v[140:141] op_sel_hi:[1,0]
	v_pk_mul_f32 v[56:57], v[56:57], v[140:141] op_sel_hi:[1,0]
	v_pk_mul_f32 v[54:55], v[54:55], v[140:141] op_sel_hi:[1,0]
	v_pk_mul_f32 v[120:121], v[120:121], v[140:141] op_sel_hi:[1,0]
	v_pk_mul_f32 v[118:119], v[118:119], v[140:141] op_sel_hi:[1,0]
	v_pk_mul_f32 v[52:53], v[52:53], v[140:141] op_sel_hi:[1,0]
	v_pk_mul_f32 v[50:51], v[50:51], v[140:141] op_sel_hi:[1,0]
	s_waitcnt vmcnt(0)
	v_ffbh_u32_e32 v128, v127
	v_min_u32_e32 v128, 32, v128
	v_lshlrev_b64 v[126:127], v128, v[126:127]
	v_min_u32_e32 v126, 1, v126
	v_or_b32_e32 v126, v127, v126
	v_cvt_f32_u32_e32 v126, v126
	v_sub_u32_e32 v127, 32, v128
	v_ldexp_f32 v126, v126, v127
	v_mul_f32_e32 v126, 0x35800000, v126
	v_fmamk_f32 v126, v126, 0x3a000000, v232
	v_cmp_gt_f32_e32 vcc, s5, v126
	v_mul_f32_e32 v127, 0x4b800000, v126
	s_nop 0
	v_cndmask_b32_e32 v126, v126, v127, vcc
	v_rsq_f32_e32 v126, v126
	s_nop 0
	v_mul_f32_e32 v127, 0x45800000, v126
	v_cndmask_b32_e32 v126, v126, v127, vcc
	v_pk_mul_f32 v[88:89], v[88:89], v[126:127] op_sel_hi:[1,0]
	v_pk_mul_f32 v[86:87], v[86:87], v[126:127] op_sel_hi:[1,0]
	v_pk_mul_f32 v[32:33], v[32:33], v[126:127] op_sel_hi:[1,0]
	v_pk_mul_f32 v[30:31], v[30:31], v[126:127] op_sel_hi:[1,0]
	v_pk_mul_f32 v[84:85], v[84:85], v[126:127] op_sel_hi:[1,0]
	v_pk_mul_f32 v[82:83], v[82:83], v[126:127] op_sel_hi:[1,0]
	v_pk_mul_f32 v[28:29], v[28:29], v[126:127] op_sel_hi:[1,0]
	v_pk_mul_f32 v[26:27], v[26:27], v[126:127] op_sel_hi:[1,0]
	v_cndmask_b32_e64 v126, 0, 1, s[26:27]
	v_cmp_lt_i32_e32 vcc, 13, v132
	v_cmp_ne_u32_e64 s[12:13], 1, v126
	s_and_saveexec_b64 s[6:7], vcc
	s_cbranch_execz .LBB0_779
	v_add3_u32 v126, v155, v154, s90
	v_lshl_add_u32 v126, v126, 6, 0
	v_add_u32_e32 v126, 0x1f200, v126
	s_and_b64 vcc, exec, s[12:13]
	ds_write_b128 v126, v[134:137]
	ds_write_b128 v126, v[54:57] offset:16
	ds_write_b128 v126, v[118:121] offset:32
	ds_write_b128 v126, v[50:53] offset:48
	ds_write_b128 v126, v[86:89] offset:4096
	ds_write_b128 v126, v[30:33] offset:4112
	ds_write_b128 v126, v[82:85] offset:4128
	ds_write_b128 v126, v[26:29] offset:4144
	s_cbranch_vccnz .LBB0_779
	s_lshl_b32 s14, s91, 2
	v_add3_u32 v128, s14, -12, v132
	v_mov_b64_e32 v[126:127], s[66:67]
	v_mad_i64_i32 v[126:127], s[14:15], v128, s49, v[126:127]
	v_ashrrev_i32_e32 v189, 31, v188
	v_lshl_add_u64 v[126:127], v[188:189], 2, v[126:127]
	global_store_dwordx4 v[126:127], v[86:89], off
	global_store_dwordx4 v[126:127], v[30:33], off offset:16
	v_add_co_u32_e32 v126, vcc, 0x5000, v126
	s_nop 1
	v_addc_co_u32_e32 v127, vcc, 0, v127, vcc
	global_store_dwordx4 v[126:127], v[82:85], off offset:2048
	global_store_dwordx4 v[126:127], v[26:29], off offset:2064
